# norm1: narrow projections rewritten (LDS-staged weights, half-swap+row-DPP reductions, 4 rows loaded together)
# speedup vs baseline: 1.0345x; 1.0345x over previous
; #define BIDX bid_opaque()
; #define GDIM gdim_opaque()
; DI void norm_phase(float* X, const float* gain, bf16_t* XN, const float* wsm, float* SM, int wave, int lane, const float* part = nullptr) {
;     const int gw = BIDX * 8 + wave, NGW = GDIM * 8;
;     f32x4 gv[4];
; #pragma unroll
;     for (int j = 0; j < 4; ++j) gv[j] = ((const f32x4*)gain)[lane + 64 * j];
;     if (wsm) { for (int row0 = gw * 4; row0 < MTOT; row0 += NGW * 4) norm_rows<4>(X, gv, XN, wsm, SM, row0, lane, part); }
;     else { for (int row = gw; row < MTOT; row += NGW) norm_rows<1>(X, gv, XN, nullptr, nullptr, row, lane, part); }
; }
.LBB0_940:
	s_andn2_b64 vcc, exec, s[8:9]
	s_cbranch_vccnz .LBB0_964
	s_waitcnt vmcnt(0)
	v_mov_b32_e32 v0, v228
	v_mov_b32_e32 v1, v228
	s_nop 0
	v_readfirstlane_b32 s0, v1
	s_ashr_i32 s1, s0, 6
	s_mov_b32 s0, s82
	s_lshl_b32 s2, s0, 3
	s_add_i32 s1, s2, s1
	s_load_dwordx2 s[10:11], s[18:19], 0xf0
	s_and_b32 s3, s1, 7
	s_mul_i32 s4, s96, 0x2400000
	v_and_b32_e32 v2, 63, v228
	v_lshlrev_b32_e32 v2, 4, v2
	s_lshl_b32 s3, s3, 10
	v_add_u32_e32 v2, s3, v2
	s_waitcnt lgkmcnt(0)
	s_add_u32 s10, s10, s4
	s_addc_u32 s11, s11, 0
	s_add_u32 s10, s10, 0xe860000
	s_addc_u32 s11, s11, 0
	s_add_i32 m0, s3, 0
	s_nop 0
	global_load_lds_dwordx4 v2, s[10:11]
	v_add_u32_e32 v2, 0x2000, v2
	s_add_i32 m0, s3, 8192
	s_nop 0
	global_load_lds_dwordx4 v2, s[10:11]
	v_add_u32_e32 v2, 0x2000, v2
	s_add_i32 m0, s3, 16384
	s_nop 0
	global_load_lds_dwordx4 v2, s[10:11]
	v_add_u32_e32 v2, 0x2000, v2
	s_add_i32 m0, s3, 24576
	s_nop 0
	global_load_lds_dwordx4 v2, s[10:11]
	v_add_u32_e32 v2, 0x2000, v2
	s_add_i32 m0, s3, 32768
	s_nop 0
	global_load_lds_dwordx4 v2, s[10:11]
	v_add_u32_e32 v2, 0x2000, v2
	s_add_i32 m0, s3, 40960
	s_nop 0
	global_load_lds_dwordx4 v2, s[10:11]
	v_add_u32_e32 v2, 0x2000, v2
	s_add_i32 m0, s3, 49152
	s_nop 0
	global_load_lds_dwordx4 v2, s[10:11]
	v_add_u32_e32 v2, 0x2000, v2
	s_add_i32 m0, s3, 57344
	s_nop 0
	global_load_lds_dwordx4 v2, s[10:11]
	v_add_u32_e32 v2, 0x2000, v2
	s_add_i32 m0, s3, 65536
	s_nop 0
	global_load_lds_dwordx4 v2, s[10:11]
	v_add_u32_e32 v2, 0x2000, v2
	s_add_i32 m0, s3, 73728
	s_nop 0
	global_load_lds_dwordx4 v2, s[10:11]
	v_add_u32_e32 v2, 0x2000, v2
	s_add_i32 m0, s3, 81920
	s_nop 0
	global_load_lds_dwordx4 v2, s[10:11]
	v_add_u32_e32 v2, 0x2000, v2
	s_add_i32 m0, s3, 90112
	s_nop 0
	global_load_lds_dwordx4 v2, s[10:11]
	v_add_u32_e32 v2, 0x2000, v2
	s_waitcnt vmcnt(0)
	s_barrier
	s_mov_b32 s0, s92
	s_cmpk_gt_i32 s1, 0x20bf
	s_cbranch_scc1 .LBB0_964
	s_load_dwordx2 s[2:3], s[18:19], 0x48
	s_load_dwordx2 s[10:11], s[18:19], 0xf0
	s_cmp_gt_i32 s96, 0
	s_cselect_b64 s[8:9], -1, 0
	s_lshl_b32 s4, s96, 10
	s_ashr_i32 s5, s4, 31
	s_lshl_b64 s[4:5], s[4:5], 2
	s_waitcnt lgkmcnt(0)
	s_add_u32 s2, s2, s4
	v_and_b32_e32 v18, 63, v0
	s_addc_u32 s3, s3, s5
	v_lshlrev_b32_e32 v32, 4, v18
	global_load_dwordx4 v[0:3], v32, s[2:3]
	global_load_dwordx4 v[4:7], v32, s[2:3] offset:1024
	global_load_dwordx4 v[8:11], v32, s[2:3] offset:2048
	global_load_dwordx4 v[12:15], v32, s[2:3] offset:3072
	v_lshlrev_b32_e32 v16, 2, v18
	v_mov_b32_e32 v17, v33
	v_lshl_add_u64 v[16:17], s[10:11], 0, v[16:17]
	s_mov_b64 s[2:3], 0x10c80000
	v_lshl_add_u64 v[34:35], v[16:17], 0, s[2:3]
	v_lshl_add_u64 v[36:37], s[10:11], 0, v[32:33]
	s_mov_b64 s[2:3], 0x1c67a000
	v_lshlrev_b32_e32 v16, 3, v18
	v_mov_b32_e32 v17, v33
	s_mul_i32 s12, s96, 0x2400000
	s_lshl_b32 s6, s1, 2
	s_lshl_b32 s0, s0, 5
	v_lshl_add_u64 v[38:39], v[36:37], 0, s[2:3]
	v_lshl_add_u64 v[16:17], s[10:11], 0, v[16:17]
	s_mov_b64 s[2:3], 0x8300000
	s_mul_hi_i32 s7, s96, 0x2400000
	v_lshl_add_u64 v[40:41], v[16:17], 0, s[2:3]
	s_add_u32 s2, s10, s12
	s_addc_u32 s3, s11, s7
	v_cmp_gt_u32_e64 s[4:5], 32, v18
	v_lshlrev_b32_e32 v42, 12, v18
	v_lshl_add_u64 v[44:45], s[2:3], 0, v[32:33]
	s_xor_b64 s[8:9], s[8:9], -1
	s_branch .LBB0_944

; template <int RB> DI void norm_rows(float* X, const f32x4 (&gv)[4], bf16_t* XN, const float* wsm, float* SM, int row0, int lane, const float* part) {
;     ...
;     for (int r = 0; r < RB; ++r) {
;         const int row = row0 + r; const f32x4* xr = (const f32x4*)(X + (size_t)row * D); float ss = 0.f;
; #pragma unroll
;         for (int j = 0; j < 4; ++j) v[r][j] = xr[lane + 64 * j];
.LBB0_944:
	s_ashr_i32 s7, s6, 31
	s_lshl_b64 s[2:3], s[6:7], 12
	v_lshl_add_u64 v[46:47], v[36:37], 0, s[2:3]
	global_load_dwordx4 v[28:31], v[46:47], off
	global_load_dwordx4 v[24:27], v[46:47], off offset:1024
	global_load_dwordx4 v[20:23], v[46:47], off offset:2048
	global_load_dwordx4 v[16:19], v[46:47], off offset:3072
	s_mov_b64 s[10:11], 0x1000
	v_lshl_add_u64 v[178:179], v[46:47], 0, s[10:11]
	s_mov_b64 s[10:11], 0x3000
	v_lshl_add_u64 v[180:181], v[46:47], 0, s[10:11]
	global_load_dwordx4 v[140:143], v[178:179], off
	global_load_dwordx4 v[136:139], v[178:179], off offset:1024
	global_load_dwordx4 v[132:135], v[178:179], off offset:2048
	global_load_dwordx4 v[128:131], v[178:179], off offset:3072
	global_load_dwordx4 v[156:159], v[180:181], off offset:-4096
	global_load_dwordx4 v[152:155], v[180:181], off offset:-3072
	global_load_dwordx4 v[148:151], v[180:181], off offset:-2048
	global_load_dwordx4 v[144:147], v[180:181], off offset:-1024
	global_load_dwordx4 v[172:175], v[180:181], off
	global_load_dwordx4 v[168:171], v[180:181], off offset:1024
	global_load_dwordx4 v[164:167], v[180:181], off offset:2048
	global_load_dwordx4 v[160:163], v[180:181], off offset:3072
	s_cmp_lt_i32 s6, 0x8000
	s_cselect_b64 s[2:3], -1, 0
	s_or_b64 s[2:3], s[8:9], s[2:3]
	s_and_b64 vcc, exec, s[2:3]
	s_cbranch_vccnz .LBB0_948
	s_movk_i32 s1, 0x8000

; __device__ __forceinline__ unsigned cvt_pk_bf16(float lo, float hi) { const f32x2_cv v = {lo, hi}; const bf16x2_cv b = __builtin_convertvector(v, bf16x2_cv); return __builtin_bit_cast(unsigned, b); }
; template <int RB> DI void norm_rows(float* X, const f32x4 (&gv)[4], bf16_t* XN, const float* wsm, float* SM, int row0, int lane, const float* part) {
;     ...
;         const int row = row0 + r; const f32x4* xr = (const f32x4*)(X + (size_t)row * D); float ss = 0.f;
; #pragma unroll
;         for (int j = 0; j < 4; ++j) v[r][j] = xr[lane + 64 * j];
;         if (part && row >= MMAIN) {
; #pragma unroll 1
;             for (int kh = 0; kh < NKSL; ++kh) { const f32x4* pr = (const f32x4*)(part + ((size_t)kh * (MTOT - MMAIN) + (row - MMAIN)) * 1024);
; #pragma unroll
;                 for (int j = 0; j < 4; ++j) v[r][j] += pr[lane + 64 * j]; }
; #pragma unroll
;             for (int j = 0; j < 4; ++j) ((f32x4*)(X + (size_t)row * D))[lane + 64 * j] = v[r][j];
;         }
; #pragma unroll
;         for (int j = 0; j < 4; ++j) ss += (v[r][j][0] * v[r][j][0] + v[r][j][1] * v[r][j][1]) + (v[r][j][2] * v[r][j][2] + v[r][j][3] * v[r][j][3]);
;         const float rs = rsqrtf(wave_sum(ss) * (1.f / D) + EPS);
;         u32x2* o = (u32x2*)(XN + (size_t)row * D);
; #pragma unroll
;         for (int j = 0; j < 4; ++j) { v[r][j] = v[r][j] * rs * gv[j]; u32x2 w; w.x = cvt_pk_bf16(v[r][j][0], v[r][j][1]); w.y = cvt_pk_bf16(v[r][j][2], v[r][j][3]); o[lane + 64 * j] = w; }
.LBB0_948:
	s_waitcnt vmcnt(15)
	v_pk_mul_f32 v[46:47], v[30:31], v[30:31]
	v_pk_mul_f32 v[48:49], v[28:29], v[28:29]
	s_waitcnt vmcnt(13)
	v_mul_f32_e32 v32, v20, v20
	v_pk_mov_b32 v[50:51], v[48:49], v[46:47] op_sel:[1,0]
	v_mov_b32_e32 v49, v47
	v_pk_add_f32 v[46:47], v[50:51], v[48:49]
	v_pk_mul_f32 v[48:49], v[26:27], v[26:27]
	v_pk_mul_f32 v[50:51], v[24:25], v[24:25]
	v_pk_add_f32 v[46:47], v[46:47], v[46:47] op_sel_hi:[0,1]
	v_pk_mov_b32 v[52:53], v[50:51], v[48:49] op_sel:[1,0]
	v_mov_b32_e32 v51, v49
	v_pk_add_f32 v[48:49], v[52:53], v[50:51]
	v_pk_fma_f32 v[50:51], v[20:21], v[20:21], v[32:33] op_sel_hi:[1,1,0]
	v_mul_f32_e32 v32, v22, v22
	v_pk_add_f32 v[48:49], v[48:49], v[48:49] op_sel_hi:[0,1]
	v_pk_fma_f32 v[52:53], v[22:23], v[22:23], v[32:33] op_sel_hi:[1,1,0]
	s_waitcnt vmcnt(12)
	v_mul_f32_e32 v50, v16, v16
	v_mul_f32_e32 v52, v17, v17
	v_mul_f32_e32 v48, v18, v18
	v_mul_f32_e32 v46, v19, v19
	v_pk_add_f32 v[50:51], v[50:51], v[52:53]
	v_pk_add_f32 v[46:47], v[48:49], v[46:47]
	s_lshl_b64 s[16:17], s[6:7], 10
	v_pk_add_f32 v[46:47], v[50:51], v[46:47]
	s_nop 0
	v_add_f32_e32 v32, v46, v47
	s_nop 1
	v_add_f32_dpp v32, v32, v32 quad_perm:[1,0,3,2] row_mask:0xf bank_mask:0xf bound_ctrl:1
	s_nop 1
	v_add_f32_dpp v32, v32, v32 quad_perm:[2,3,0,1] row_mask:0xf bank_mask:0xf bound_ctrl:1
	s_nop 1
	v_add_f32_dpp v32, v32, v32 row_half_mirror row_mask:0xf bank_mask:0xf bound_ctrl:1
	s_nop 1
	v_add_f32_dpp v32, v32, v32 row_mirror row_mask:0xf bank_mask:0xf bound_ctrl:1
	s_nop 0
	v_readlane_b32 s1, v32, 16
	v_readlane_b32 s10, v32, 48
	v_readlane_b32 s2, v32, 0
	v_readlane_b32 s3, v32, 32
	v_mov_b32_e32 v46, s1
	v_mov_b32_e32 v47, s10
	v_pk_add_f32 v[46:47], s[2:3], v[46:47]
	s_nop 0
	v_add_f32_e32 v32, v46, v47
	v_fmamk_f32 v32, v32, 0x3a800000, v229
	v_mul_f32_e32 v43, 0x4b800000, v32
	v_cmp_gt_f32_e32 vcc, s81, v32
	s_nop 1
	v_cndmask_b32_e32 v32, v32, v43, vcc
	v_rsq_f32_e32 v32, v32
	s_nop 0
	v_mul_f32_e32 v43, 0x45800000, v32
	v_cndmask_b32_e32 v32, v32, v43, vcc
	v_pk_mul_f32 v[30:31], v[30:31], v[32:33] op_sel_hi:[1,0]
	v_pk_mul_f32 v[28:29], v[28:29], v[32:33] op_sel_hi:[1,0]
	v_pk_mul_f32 v[46:47], v[2:3], v[30:31]
	v_lshl_add_u64 v[30:31], s[16:17], 1, v[40:41]
	v_pk_mul_f32 v[24:25], v[24:25], v[32:33] op_sel_hi:[1,0]
	v_pk_mul_f32 v[26:27], v[26:27], v[32:33] op_sel_hi:[1,0]
	v_pk_mul_f32 v[20:21], v[20:21], v[32:33] op_sel_hi:[1,0]
	v_pk_mul_f32 v[22:23], v[22:23], v[32:33] op_sel_hi:[1,0]
	v_pk_mul_f32 v[16:17], v[16:17], v[32:33] op_sel_hi:[1,0]
	v_pk_mul_f32 v[18:19], v[18:19], v[32:33] op_sel_hi:[1,0]
	s_or_b32 s16, s6, 1
	v_pk_mul_f32 v[48:49], v[0:1], v[28:29]
	v_pk_mul_f32 v[50:51], v[6:7], v[26:27]
	v_pk_mul_f32 v[52:53], v[4:5], v[24:25]
	v_pk_mul_f32 v[54:55], v[10:11], v[22:23]
	v_pk_mul_f32 v[56:57], v[8:9], v[20:21]
	v_pk_mul_f32 v[58:59], v[14:15], v[18:19]
	v_pk_mul_f32 v[60:61], v[12:13], v[16:17]
	s_ashr_i32 s17, s16, 31
	v_cvt_pk_bf16_f32 v28, v48, v49
	v_cvt_pk_bf16_f32 v29, v46, v47
	v_cvt_pk_bf16_f32 v24, v52, v53
	v_cvt_pk_bf16_f32 v25, v50, v51
	v_cvt_pk_bf16_f32 v20, v56, v57
	v_cvt_pk_bf16_f32 v21, v54, v55
	v_cvt_pk_bf16_f32 v16, v60, v61
	v_cvt_pk_bf16_f32 v17, v58, v59
	s_lshl_b64 s[2:3], s[16:17], 12
	global_store_dwordx2 v[30:31], v[28:29], off
	global_store_dwordx2 v[30:31], v[24:25], off offset:512
	global_store_dwordx2 v[30:31], v[20:21], off offset:1024
	global_store_dwordx2 v[30:31], v[16:17], off offset:1536
	v_lshl_add_u64 v[62:63], v[36:37], 0, s[2:3]
	s_waitcnt vmcnt(12)
	v_mov_b64_e32 v[16:17], v[128:129]
	v_mov_b64_e32 v[18:19], v[130:131]
	v_mov_b64_e32 v[20:21], v[132:133]
	v_mov_b64_e32 v[22:23], v[134:135]
	v_mov_b64_e32 v[24:25], v[136:137]
	v_mov_b64_e32 v[26:27], v[138:139]
	v_mov_b64_e32 v[28:29], v[140:141]
	v_mov_b64_e32 v[30:31], v[142:143]
	s_cmpk_lt_i32 s6, 0x7fff
	s_cselect_b64 s[2:3], -1, 0
	s_or_b64 s[2:3], s[8:9], s[2:3]
	s_and_b64 vcc, exec, s[2:3]
	s_cbranch_vccnz .LBB0_952
	s_movk_i32 s1, 0x8001

; __device__ __forceinline__ unsigned cvt_pk_bf16(float lo, float hi) { const f32x2_cv v = {lo, hi}; const bf16x2_cv b = __builtin_convertvector(v, bf16x2_cv); return __builtin_bit_cast(unsigned, b); }
; template <int RB> DI void norm_rows(float* X, const f32x4 (&gv)[4], bf16_t* XN, const float* wsm, float* SM, int row0, int lane, const float* part) {
;     ...
;         const int row = row0 + r; const f32x4* xr = (const f32x4*)(X + (size_t)row * D); float ss = 0.f;
; #pragma unroll
;         for (int j = 0; j < 4; ++j) v[r][j] = xr[lane + 64 * j];
;         if (part && row >= MMAIN) {
; #pragma unroll 1
;             for (int kh = 0; kh < NKSL; ++kh) { const f32x4* pr = (const f32x4*)(part + ((size_t)kh * (MTOT - MMAIN) + (row - MMAIN)) * 1024);
; #pragma unroll
;                 for (int j = 0; j < 4; ++j) v[r][j] += pr[lane + 64 * j]; }
; #pragma unroll
;             for (int j = 0; j < 4; ++j) ((f32x4*)(X + (size_t)row * D))[lane + 64 * j] = v[r][j];
;         }
; #pragma unroll
;         for (int j = 0; j < 4; ++j) ss += (v[r][j][0] * v[r][j][0] + v[r][j][1] * v[r][j][1]) + (v[r][j][2] * v[r][j][2] + v[r][j][3] * v[r][j][3]);
;         const float rs = rsqrtf(wave_sum(ss) * (1.f / D) + EPS);
;         u32x2* o = (u32x2*)(XN + (size_t)row * D);
; #pragma unroll
;         for (int j = 0; j < 4; ++j) { v[r][j] = v[r][j] * rs * gv[j]; u32x2 w; w.x = cvt_pk_bf16(v[r][j][0], v[r][j][1]); w.y = cvt_pk_bf16(v[r][j][2], v[r][j][3]); o[lane + 64 * j] = w; }
.LBB0_952:
	v_pk_mul_f32 v[62:63], v[30:31], v[30:31]
	v_pk_mul_f32 v[64:65], v[28:29], v[28:29]
	v_mul_f32_e32 v32, v20, v20
	v_pk_mov_b32 v[66:67], v[64:65], v[62:63] op_sel:[1,0]
	v_mov_b32_e32 v65, v63
	v_pk_add_f32 v[62:63], v[66:67], v[64:65]
	v_pk_mul_f32 v[64:65], v[26:27], v[26:27]
	v_pk_mul_f32 v[66:67], v[24:25], v[24:25]
	v_pk_add_f32 v[62:63], v[62:63], v[62:63] op_sel_hi:[0,1]
	v_pk_mov_b32 v[68:69], v[66:67], v[64:65] op_sel:[1,0]
	v_mov_b32_e32 v67, v65
	v_pk_add_f32 v[64:65], v[68:69], v[66:67]
	v_pk_fma_f32 v[66:67], v[20:21], v[20:21], v[32:33] op_sel_hi:[1,1,0]
	v_mul_f32_e32 v32, v22, v22
	v_pk_add_f32 v[64:65], v[64:65], v[64:65] op_sel_hi:[0,1]
	v_pk_fma_f32 v[68:69], v[22:23], v[22:23], v[32:33] op_sel_hi:[1,1,0]
	v_mul_f32_e32 v66, v16, v16
	v_mul_f32_e32 v68, v17, v17
	v_mul_f32_e32 v64, v18, v18
	v_mul_f32_e32 v62, v19, v19
	v_pk_add_f32 v[66:67], v[66:67], v[68:69]
	v_pk_add_f32 v[62:63], v[64:65], v[62:63]
	s_or_b32 s38, s6, 2
	v_pk_add_f32 v[62:63], v[66:67], v[62:63]
	s_lshl_b64 s[20:21], s[16:17], 10
	v_add_f32_e32 v32, v62, v63
	s_ashr_i32 s39, s38, 31
	s_nop 0
	v_add_f32_dpp v32, v32, v32 quad_perm:[1,0,3,2] row_mask:0xf bank_mask:0xf bound_ctrl:1
	s_nop 1
	v_add_f32_dpp v32, v32, v32 quad_perm:[2,3,0,1] row_mask:0xf bank_mask:0xf bound_ctrl:1
	s_nop 1
	v_add_f32_dpp v32, v32, v32 row_half_mirror row_mask:0xf bank_mask:0xf bound_ctrl:1
	s_nop 1
	v_add_f32_dpp v32, v32, v32 row_mirror row_mask:0xf bank_mask:0xf bound_ctrl:1
	s_nop 0
	v_readlane_b32 s1, v32, 16
	v_readlane_b32 s10, v32, 48
	v_readlane_b32 s2, v32, 0
	v_readlane_b32 s3, v32, 32
	v_mov_b32_e32 v62, s1
	v_mov_b32_e32 v63, s10
	v_pk_add_f32 v[62:63], s[2:3], v[62:63]
	s_lshl_b64 s[2:3], s[38:39], 12
	v_add_f32_e32 v32, v62, v63
	v_fmamk_f32 v32, v32, 0x3a800000, v229
	v_mul_f32_e32 v43, 0x4b800000, v32
	v_cmp_gt_f32_e32 vcc, s81, v32
	v_lshl_add_u64 v[78:79], v[36:37], 0, s[2:3]
	s_cmpk_lt_i32 s6, 0x7ffe
	v_cndmask_b32_e32 v32, v32, v43, vcc
	v_rsq_f32_e32 v32, v32
	s_cselect_b64 s[2:3], -1, 0
	s_or_b64 s[2:3], s[8:9], s[2:3]
	v_mul_f32_e32 v43, 0x45800000, v32
	v_cndmask_b32_e32 v32, v32, v43, vcc
	v_pk_mul_f32 v[28:29], v[28:29], v[32:33] op_sel_hi:[1,0]
	v_pk_mul_f32 v[30:31], v[30:31], v[32:33] op_sel_hi:[1,0]
	v_pk_mul_f32 v[24:25], v[24:25], v[32:33] op_sel_hi:[1,0]
	v_pk_mul_f32 v[26:27], v[26:27], v[32:33] op_sel_hi:[1,0]
	v_pk_mul_f32 v[20:21], v[20:21], v[32:33] op_sel_hi:[1,0]
	v_pk_mul_f32 v[22:23], v[22:23], v[32:33] op_sel_hi:[1,0]
	v_pk_mul_f32 v[16:17], v[16:17], v[32:33] op_sel_hi:[1,0]
	v_pk_mul_f32 v[18:19], v[18:19], v[32:33] op_sel_hi:[1,0]
	v_pk_mul_f32 v[62:63], v[2:3], v[30:31]
	v_pk_mul_f32 v[64:65], v[0:1], v[28:29]
	v_pk_mul_f32 v[66:67], v[6:7], v[26:27]
	v_pk_mul_f32 v[68:69], v[4:5], v[24:25]
	v_pk_mul_f32 v[70:71], v[10:11], v[22:23]
	v_pk_mul_f32 v[72:73], v[8:9], v[20:21]
	v_pk_mul_f32 v[74:75], v[14:15], v[18:19]
	v_pk_mul_f32 v[76:77], v[12:13], v[16:17]
	v_cvt_pk_bf16_f32 v28, v64, v65
	v_cvt_pk_bf16_f32 v29, v62, v63
	v_lshl_add_u64 v[30:31], s[20:21], 1, v[40:41]
	v_cvt_pk_bf16_f32 v24, v68, v69
	v_cvt_pk_bf16_f32 v25, v66, v67
	v_cvt_pk_bf16_f32 v20, v72, v73
	v_cvt_pk_bf16_f32 v21, v70, v71
	v_cvt_pk_bf16_f32 v16, v76, v77
	v_cvt_pk_bf16_f32 v17, v74, v75
	global_store_dwordx2 v[30:31], v[28:29], off
	global_store_dwordx2 v[30:31], v[24:25], off offset:512
	global_store_dwordx2 v[30:31], v[20:21], off offset:1024
	global_store_dwordx2 v[30:31], v[16:17], off offset:1536
	s_waitcnt vmcnt(12)
	v_mov_b64_e32 v[16:17], v[144:145]
	v_mov_b64_e32 v[18:19], v[146:147]
	v_mov_b64_e32 v[20:21], v[148:149]
	v_mov_b64_e32 v[22:23], v[150:151]
	v_mov_b64_e32 v[24:25], v[152:153]
	v_mov_b64_e32 v[26:27], v[154:155]
	v_mov_b64_e32 v[28:29], v[156:157]
	v_mov_b64_e32 v[30:31], v[158:159]
	s_and_b64 vcc, exec, s[2:3]
	s_cbranch_vccnz .LBB0_956
	s_movk_i32 s1, 0x8002

; __device__ __forceinline__ unsigned cvt_pk_bf16(float lo, float hi) { const f32x2_cv v = {lo, hi}; const bf16x2_cv b = __builtin_convertvector(v, bf16x2_cv); return __builtin_bit_cast(unsigned, b); }
; template <int RB> DI void norm_rows(float* X, const f32x4 (&gv)[4], bf16_t* XN, const float* wsm, float* SM, int row0, int lane, const float* part) {
;     ...
;         const int row = row0 + r; const f32x4* xr = (const f32x4*)(X + (size_t)row * D); float ss = 0.f;
; #pragma unroll
;         for (int j = 0; j < 4; ++j) v[r][j] = xr[lane + 64 * j];
;         if (part && row >= MMAIN) {
; #pragma unroll 1
;             for (int kh = 0; kh < NKSL; ++kh) { const f32x4* pr = (const f32x4*)(part + ((size_t)kh * (MTOT - MMAIN) + (row - MMAIN)) * 1024);
; #pragma unroll
;                 for (int j = 0; j < 4; ++j) v[r][j] += pr[lane + 64 * j]; }
; #pragma unroll
;             for (int j = 0; j < 4; ++j) ((f32x4*)(X + (size_t)row * D))[lane + 64 * j] = v[r][j];
;         }
; #pragma unroll
;         for (int j = 0; j < 4; ++j) ss += (v[r][j][0] * v[r][j][0] + v[r][j][1] * v[r][j][1]) + (v[r][j][2] * v[r][j][2] + v[r][j][3] * v[r][j][3]);
;         const float rs = rsqrtf(wave_sum(ss) * (1.f / D) + EPS);
;         u32x2* o = (u32x2*)(XN + (size_t)row * D);
; #pragma unroll
;         for (int j = 0; j < 4; ++j) { v[r][j] = v[r][j] * rs * gv[j]; u32x2 w; w.x = cvt_pk_bf16(v[r][j][0], v[r][j][1]); w.y = cvt_pk_bf16(v[r][j][2], v[r][j][3]); o[lane + 64 * j] = w; }
.LBB0_956:
	v_pk_mul_f32 v[78:79], v[30:31], v[30:31]
	v_pk_mul_f32 v[80:81], v[28:29], v[28:29]
	v_mul_f32_e32 v32, v20, v20
	v_pk_mov_b32 v[82:83], v[80:81], v[78:79] op_sel:[1,0]
	v_mov_b32_e32 v81, v79
	v_pk_add_f32 v[78:79], v[82:83], v[80:81]
	v_pk_mul_f32 v[80:81], v[26:27], v[26:27]
	v_pk_mul_f32 v[82:83], v[24:25], v[24:25]
	v_pk_add_f32 v[78:79], v[78:79], v[78:79] op_sel_hi:[0,1]
	v_pk_mov_b32 v[84:85], v[82:83], v[80:81] op_sel:[1,0]
	v_mov_b32_e32 v83, v81
	v_pk_add_f32 v[80:81], v[84:85], v[82:83]
	v_pk_fma_f32 v[82:83], v[20:21], v[20:21], v[32:33] op_sel_hi:[1,1,0]
	v_mul_f32_e32 v32, v22, v22
	v_pk_add_f32 v[80:81], v[80:81], v[80:81] op_sel_hi:[0,1]
	v_pk_fma_f32 v[84:85], v[22:23], v[22:23], v[32:33] op_sel_hi:[1,1,0]
	v_mul_f32_e32 v82, v16, v16
	v_mul_f32_e32 v84, v17, v17
	v_mul_f32_e32 v80, v18, v18
	v_mul_f32_e32 v78, v19, v19
	v_pk_add_f32 v[82:83], v[82:83], v[84:85]
	v_pk_add_f32 v[78:79], v[80:81], v[78:79]
	s_or_b32 s40, s6, 3
	v_pk_add_f32 v[78:79], v[82:83], v[78:79]
	s_lshl_b64 s[20:21], s[38:39], 10
	v_add_f32_e32 v32, v78, v79
	s_ashr_i32 s41, s40, 31
	s_nop 0
	v_add_f32_dpp v32, v32, v32 quad_perm:[1,0,3,2] row_mask:0xf bank_mask:0xf bound_ctrl:1
	s_nop 1
	v_add_f32_dpp v32, v32, v32 quad_perm:[2,3,0,1] row_mask:0xf bank_mask:0xf bound_ctrl:1
	s_nop 1
	v_add_f32_dpp v32, v32, v32 row_half_mirror row_mask:0xf bank_mask:0xf bound_ctrl:1
	s_nop 1
	v_add_f32_dpp v32, v32, v32 row_mirror row_mask:0xf bank_mask:0xf bound_ctrl:1
	s_nop 0
	v_readlane_b32 s1, v32, 16
	v_readlane_b32 s10, v32, 48
	v_readlane_b32 s2, v32, 0
	v_readlane_b32 s3, v32, 32
	v_mov_b32_e32 v78, s1
	v_mov_b32_e32 v79, s10
	v_pk_add_f32 v[78:79], s[2:3], v[78:79]
	s_lshl_b64 s[2:3], s[40:41], 12
	v_add_f32_e32 v32, v78, v79
	v_fmamk_f32 v32, v32, 0x3a800000, v229
	v_mul_f32_e32 v43, 0x4b800000, v32
	v_cmp_gt_f32_e32 vcc, s81, v32
	v_lshl_add_u64 v[94:95], v[36:37], 0, s[2:3]
	s_cmpk_lt_i32 s6, 0x7ffd
	v_cndmask_b32_e32 v32, v32, v43, vcc
	v_rsq_f32_e32 v32, v32
	s_cselect_b64 s[2:3], -1, 0
	s_or_b64 s[2:3], s[8:9], s[2:3]
	v_mul_f32_e32 v43, 0x45800000, v32
	v_cndmask_b32_e32 v32, v32, v43, vcc
	v_pk_mul_f32 v[28:29], v[28:29], v[32:33] op_sel_hi:[1,0]
	v_pk_mul_f32 v[30:31], v[30:31], v[32:33] op_sel_hi:[1,0]
	v_pk_mul_f32 v[24:25], v[24:25], v[32:33] op_sel_hi:[1,0]
	v_pk_mul_f32 v[26:27], v[26:27], v[32:33] op_sel_hi:[1,0]
	v_pk_mul_f32 v[20:21], v[20:21], v[32:33] op_sel_hi:[1,0]
	v_pk_mul_f32 v[22:23], v[22:23], v[32:33] op_sel_hi:[1,0]
	v_pk_mul_f32 v[16:17], v[16:17], v[32:33] op_sel_hi:[1,0]
	v_pk_mul_f32 v[18:19], v[18:19], v[32:33] op_sel_hi:[1,0]
	v_pk_mul_f32 v[78:79], v[2:3], v[30:31]
	v_pk_mul_f32 v[80:81], v[0:1], v[28:29]
	v_pk_mul_f32 v[82:83], v[6:7], v[26:27]
	v_pk_mul_f32 v[84:85], v[4:5], v[24:25]
	v_pk_mul_f32 v[86:87], v[10:11], v[22:23]
	v_pk_mul_f32 v[88:89], v[8:9], v[20:21]
	v_pk_mul_f32 v[90:91], v[14:15], v[18:19]
	v_pk_mul_f32 v[92:93], v[12:13], v[16:17]
	v_cvt_pk_bf16_f32 v28, v80, v81
	v_cvt_pk_bf16_f32 v29, v78, v79
	v_lshl_add_u64 v[30:31], s[20:21], 1, v[40:41]
	v_cvt_pk_bf16_f32 v24, v84, v85
	v_cvt_pk_bf16_f32 v25, v82, v83
	v_cvt_pk_bf16_f32 v20, v88, v89
	v_cvt_pk_bf16_f32 v21, v86, v87
	v_cvt_pk_bf16_f32 v16, v92, v93
	v_cvt_pk_bf16_f32 v17, v90, v91
	global_store_dwordx2 v[30:31], v[28:29], off
	global_store_dwordx2 v[30:31], v[24:25], off offset:512
	global_store_dwordx2 v[30:31], v[20:21], off offset:1024
	global_store_dwordx2 v[30:31], v[16:17], off offset:1536
	s_waitcnt vmcnt(12)
	v_mov_b64_e32 v[16:17], v[160:161]
	v_mov_b64_e32 v[18:19], v[162:163]
	v_mov_b64_e32 v[20:21], v[164:165]
	v_mov_b64_e32 v[22:23], v[166:167]
	v_mov_b64_e32 v[24:25], v[168:169]
	v_mov_b64_e32 v[26:27], v[170:171]
	v_mov_b64_e32 v[28:29], v[172:173]
	v_mov_b64_e32 v[30:31], v[174:175]
	s_and_b64 vcc, exec, s[2:3]
	s_cbranch_vccnz .LBB0_960
	s_movk_i32 s1, 0x8003

; __device__ __forceinline__ unsigned cvt_pk_bf16(float lo, float hi) { const f32x2_cv v = {lo, hi}; const bf16x2_cv b = __builtin_convertvector(v, bf16x2_cv); return __builtin_bit_cast(unsigned, b); }
; template <int RB> DI void norm_rows(float* X, const f32x4 (&gv)[4], bf16_t* XN, const float* wsm, float* SM, int row0, int lane, const float* part) {
;     ...
;         const int row = row0 + r; const f32x4* xr = (const f32x4*)(X + (size_t)row * D); float ss = 0.f;
; #pragma unroll
;         for (int j = 0; j < 4; ++j) v[r][j] = xr[lane + 64 * j];
;         if (part && row >= MMAIN) {
; #pragma unroll 1
;             for (int kh = 0; kh < NKSL; ++kh) { const f32x4* pr = (const f32x4*)(part + ((size_t)kh * (MTOT - MMAIN) + (row - MMAIN)) * 1024);
; #pragma unroll
;                 for (int j = 0; j < 4; ++j) v[r][j] += pr[lane + 64 * j]; }
; #pragma unroll
;             for (int j = 0; j < 4; ++j) ((f32x4*)(X + (size_t)row * D))[lane + 64 * j] = v[r][j];
;         }
; #pragma unroll
;         for (int j = 0; j < 4; ++j) ss += (v[r][j][0] * v[r][j][0] + v[r][j][1] * v[r][j][1]) + (v[r][j][2] * v[r][j][2] + v[r][j][3] * v[r][j][3]);
;         const float rs = rsqrtf(wave_sum(ss) * (1.f / D) + EPS);
;         u32x2* o = (u32x2*)(XN + (size_t)row * D);
; #pragma unroll
;         for (int j = 0; j < 4; ++j) { v[r][j] = v[r][j] * rs * gv[j]; u32x2 w; w.x = cvt_pk_bf16(v[r][j][0], v[r][j][1]); w.y = cvt_pk_bf16(v[r][j][2], v[r][j][3]); o[lane + 64 * j] = w; }
;     ...
;         float mine[RB];
; #pragma unroll
;         for (int r = 0; r < RB; ++r) mine[r] = 0.f;
; #pragma unroll 1
;         for (int jj = 0; jj < 24; ++jj) {
;             const f32x4* wr = (const f32x4*)(wsm + (size_t)jj * D); f32x4 w[4];
; #pragma unroll
;             for (int j = 0; j < 4; ++j) w[j] = wr[lane + 64 * j];
.LBB0_960:
	v_pk_mul_f32 v[94:95], v[30:31], v[30:31]
	v_pk_mul_f32 v[96:97], v[28:29], v[28:29]
	v_mul_f32_e32 v32, v16, v16
	v_pk_mov_b32 v[98:99], v[96:97], v[94:95] op_sel:[1,0]
	v_mov_b32_e32 v97, v95
	v_pk_add_f32 v[94:95], v[98:99], v[96:97]
	v_pk_mul_f32 v[96:97], v[26:27], v[26:27]
	v_pk_mul_f32 v[98:99], v[24:25], v[24:25]
	v_mul_f32_e32 v43, v17, v17
	v_pk_mov_b32 v[100:101], v[98:99], v[96:97] op_sel:[1,0]
	v_mov_b32_e32 v99, v97
	v_pk_add_f32 v[96:97], v[100:101], v[98:99]
	v_pk_add_f32 v[94:95], v[94:95], v[94:95] op_sel:[0,1] op_sel_hi:[1,0]
	v_pk_add_f32 v[96:97], v[96:97], v[96:97] op_sel:[0,1] op_sel_hi:[1,0]
	v_mov_b32_e32 v95, v32
	v_mov_b32_e32 v97, v43
	v_mul_f32_e32 v32, v21, v21
	v_mul_f32_e32 v98, v18, v18
	v_pk_add_f32 v[94:95], v[94:95], v[96:97]
	v_pk_fma_f32 v[96:97], v[20:21], v[20:21], v[32:33] op_sel_hi:[1,1,0]
	v_mul_f32_e32 v32, v23, v23
	v_mul_f32_e32 v100, v19, v19
	v_mov_b32_e32 v97, v98
	v_pk_fma_f32 v[98:99], v[22:23], v[22:23], v[32:33] op_sel_hi:[1,1,0]
	s_lshl_b64 s[20:21], s[40:41], 10
	v_mov_b32_e32 v99, v100
	v_pk_add_f32 v[96:97], v[96:97], v[98:99]
	s_mov_b64 s[42:43], 0
	v_pk_add_f32 v[94:95], v[94:95], v[96:97]
	v_mov_b32_e32 v110, 0
	v_add_f32_e32 v32, v94, v95
	v_mov_b32_e32 v111, 0
	s_nop 0
	v_add_f32_dpp v32, v32, v32 quad_perm:[1,0,3,2] row_mask:0xf bank_mask:0xf bound_ctrl:1
	s_nop 1
	v_add_f32_dpp v32, v32, v32 quad_perm:[2,3,0,1] row_mask:0xf bank_mask:0xf bound_ctrl:1
	s_nop 1
	v_add_f32_dpp v32, v32, v32 row_half_mirror row_mask:0xf bank_mask:0xf bound_ctrl:1
	s_nop 1
	v_add_f32_dpp v32, v32, v32 row_mirror row_mask:0xf bank_mask:0xf bound_ctrl:1
	s_nop 0
	v_readlane_b32 s1, v32, 16
	v_readlane_b32 s10, v32, 48
	v_readlane_b32 s2, v32, 0
	v_readlane_b32 s3, v32, 32
	v_mov_b32_e32 v94, s1
	v_mov_b32_e32 v95, s10
	v_pk_add_f32 v[94:95], s[2:3], v[94:95]
	s_nop 0
	v_add_f32_e32 v32, v94, v95
	v_fmamk_f32 v32, v32, 0x3a800000, v229
	v_mul_f32_e32 v43, 0x4b800000, v32
	v_cmp_gt_f32_e32 vcc, s81, v32
	s_nop 1
	v_cndmask_b32_e32 v32, v32, v43, vcc
	v_rsq_f32_e32 v32, v32
	s_nop 0
	v_mul_f32_e32 v43, 0x45800000, v32
	v_cndmask_b32_e32 v32, v32, v43, vcc
	v_pk_mul_f32 v[28:29], v[28:29], v[32:33] op_sel_hi:[1,0]
	v_pk_mul_f32 v[30:31], v[30:31], v[32:33] op_sel_hi:[1,0]
	v_pk_mul_f32 v[24:25], v[24:25], v[32:33] op_sel_hi:[1,0]
	v_pk_mul_f32 v[26:27], v[26:27], v[32:33] op_sel_hi:[1,0]
	v_pk_mul_f32 v[20:21], v[20:21], v[32:33] op_sel_hi:[1,0]
	v_pk_mul_f32 v[22:23], v[22:23], v[32:33] op_sel_hi:[1,0]
	v_pk_mul_f32 v[16:17], v[16:17], v[32:33] op_sel_hi:[1,0]
	v_pk_mul_f32 v[18:19], v[18:19], v[32:33] op_sel_hi:[1,0]
	v_pk_mul_f32 v[94:95], v[2:3], v[30:31]
	v_pk_mul_f32 v[96:97], v[0:1], v[28:29]
	v_pk_mul_f32 v[98:99], v[6:7], v[26:27]
	v_pk_mul_f32 v[100:101], v[4:5], v[24:25]
	v_pk_mul_f32 v[102:103], v[10:11], v[22:23]
	v_pk_mul_f32 v[104:105], v[8:9], v[20:21]
	v_pk_mul_f32 v[106:107], v[14:15], v[18:19]
	v_pk_mul_f32 v[108:109], v[12:13], v[16:17]
	v_cvt_pk_bf16_f32 v28, v96, v97
	v_cvt_pk_bf16_f32 v29, v94, v95
	v_lshl_add_u64 v[30:31], s[20:21], 1, v[40:41]
	v_cvt_pk_bf16_f32 v24, v100, v101
	v_cvt_pk_bf16_f32 v25, v98, v99
	v_cvt_pk_bf16_f32 v20, v104, v105
	v_cvt_pk_bf16_f32 v21, v102, v103
	v_cvt_pk_bf16_f32 v16, v108, v109
	v_cvt_pk_bf16_f32 v17, v106, v107
	v_mov_b32_e32 v32, 0
	v_mov_b32_e32 v43, 0
	global_store_dwordx2 v[30:31], v[28:29], off
	global_store_dwordx2 v[30:31], v[24:25], off offset:512
	global_store_dwordx2 v[30:31], v[20:21], off offset:1024
	global_store_dwordx2 v[30:31], v[16:17], off offset:1536
	v_bfe_u32 v126, v42, 12, 4
	v_lshrrev_b32_e32 v182, 8, v42
	ds_read_b128 v[16:19], v182
	ds_read_b128 v[20:23], v182 offset:1024
	ds_read_b128 v[24:27], v182 offset:2048
	ds_read_b128 v[28:31], v182 offset:3072
	ds_read_b128 v[128:131], v182 offset:4096
	ds_read_b128 v[132:135], v182 offset:5120
	ds_read_b128 v[136:139], v182 offset:6144
	ds_read_b128 v[140:143], v182 offset:7168
	s_mov_b32 s1, 0
.Lnp_trip:
	s_lshl_b32 s10, s1, 2
	s_and_b32 s10, s10, 12
	ds_read_b128 v[144:147], v182 offset:8192
	ds_read_b128 v[148:151], v182 offset:9216
	ds_read_b128 v[152:155], v182 offset:10240
	ds_read_b128 v[156:159], v182 offset:11264
	v_cmp_eq_u32_e32 vcc, s10, v126
	s_waitcnt lgkmcnt(8)
; template <int RB> DI void norm_rows(float* X, const f32x4 (&gv)[4], bf16_t* XN, const float* wsm, float* SM, int row0, int lane, const float* part) {
;     ...
;         for (int jj = 0; jj < 24; ++jj) {
;             const f32x4* wr = (const f32x4*)(wsm + (size_t)jj * D); f32x4 w[4];
; #pragma unroll
;             for (int j = 0; j < 4; ++j) w[j] = wr[lane + 64 * j];
; #pragma unroll
;             for (int r = 0; r < RB; ++r) { float p = 0.f;
; #pragma unroll
;                 for (int j = 0; j < 4; ++j) p += (v[r][j][0] * w[j][0] + v[r][j][1] * w[j][1]) + (v[r][j][2] * w[j][2] + v[r][j][3] * w[j][3]);
;                 p = wave_sum(p); if (lane == jj) mine[r] = p; }
	v_pk_mul_f32 v[112:113], v[46:47], v[18:19]
	v_pk_mul_f32 v[114:115], v[62:63], v[18:19]
	v_pk_mul_f32 v[116:117], v[78:79], v[18:19]
	v_pk_mul_f32 v[118:119], v[94:95], v[18:19]
	v_pk_fma_f32 v[112:113], v[48:49], v[16:17], v[112:113]
	v_pk_fma_f32 v[114:115], v[64:65], v[16:17], v[114:115]
	v_pk_fma_f32 v[116:117], v[80:81], v[16:17], v[116:117]
	v_pk_fma_f32 v[118:119], v[96:97], v[16:17], v[118:119]
	v_pk_fma_f32 v[112:113], v[50:51], v[22:23], v[112:113]
	v_pk_fma_f32 v[114:115], v[66:67], v[22:23], v[114:115]
	v_pk_fma_f32 v[116:117], v[82:83], v[22:23], v[116:117]
	v_pk_fma_f32 v[118:119], v[98:99], v[22:23], v[118:119]
	v_pk_fma_f32 v[112:113], v[52:53], v[20:21], v[112:113]
	v_pk_fma_f32 v[114:115], v[68:69], v[20:21], v[114:115]
	v_pk_fma_f32 v[116:117], v[84:85], v[20:21], v[116:117]
	v_pk_fma_f32 v[118:119], v[100:101], v[20:21], v[118:119]
	v_pk_fma_f32 v[112:113], v[54:55], v[26:27], v[112:113]
	v_pk_fma_f32 v[114:115], v[70:71], v[26:27], v[114:115]
	v_pk_fma_f32 v[116:117], v[86:87], v[26:27], v[116:117]
	v_pk_fma_f32 v[118:119], v[102:103], v[26:27], v[118:119]
	v_pk_fma_f32 v[112:113], v[56:57], v[24:25], v[112:113]
	v_pk_fma_f32 v[114:115], v[72:73], v[24:25], v[114:115]
	v_pk_fma_f32 v[116:117], v[88:89], v[24:25], v[116:117]
	v_pk_fma_f32 v[118:119], v[104:105], v[24:25], v[118:119]
	v_pk_fma_f32 v[112:113], v[58:59], v[30:31], v[112:113]
	v_pk_fma_f32 v[114:115], v[74:75], v[30:31], v[114:115]
	v_pk_fma_f32 v[116:117], v[90:91], v[30:31], v[116:117]
	v_pk_fma_f32 v[118:119], v[106:107], v[30:31], v[118:119]
	v_pk_fma_f32 v[112:113], v[60:61], v[28:29], v[112:113]
	v_pk_fma_f32 v[114:115], v[76:77], v[28:29], v[114:115]
	v_pk_fma_f32 v[116:117], v[92:93], v[28:29], v[116:117]
	v_pk_fma_f32 v[118:119], v[108:109], v[28:29], v[118:119]
	v_add_f32_e32 v122, v116, v117
	v_add_f32_e32 v123, v118, v119
	v_add_f32_e32 v120, v112, v113
	v_add_f32_e32 v121, v114, v115
	v_permlane32_swap_b32_e32 v122, v123
	s_nop 0
	v_permlane32_swap_b32_e32 v120, v121
	v_add_f32_e32 v125, v122, v123
	v_add_f32_e32 v124, v120, v121
	s_nop 0
	v_add_f32_dpp v125, v125, v125 quad_perm:[1,0,3,2] row_mask:0xf bank_mask:0xf bound_ctrl:1
	v_add_f32_dpp v124, v124, v124 quad_perm:[1,0,3,2] row_mask:0xf bank_mask:0xf bound_ctrl:1
	s_nop 0
	v_add_f32_dpp v125, v125, v125 quad_perm:[2,3,0,1] row_mask:0xf bank_mask:0xf bound_ctrl:1
	v_add_f32_dpp v124, v124, v124 quad_perm:[2,3,0,1] row_mask:0xf bank_mask:0xf bound_ctrl:1
	s_nop 0
	v_add_f32_dpp v125, v125, v125 row_half_mirror row_mask:0xf bank_mask:0xf bound_ctrl:1
	v_add_f32_dpp v124, v124, v124 row_half_mirror row_mask:0xf bank_mask:0xf bound_ctrl:1
	s_nop 0
	v_add_f32_dpp v125, v125, v125 row_mirror row_mask:0xf bank_mask:0xf bound_ctrl:1
	v_add_f32_dpp v124, v124, v124 row_mirror row_mask:0xf bank_mask:0xf bound_ctrl:1
	s_nop 0
	v_add_f32_dpp v125, v125, v125 row_bcast:15 row_mask:0xa bank_mask:0xf
	v_add_f32_dpp v124, v124, v124 row_bcast:15 row_mask:0xa bank_mask:0xf
	v_cndmask_b32_e32 v111, v111, v125, vcc
	v_cndmask_b32_e32 v110, v110, v124, vcc
	ds_read_b128 v[160:163], v182 offset:12288
	ds_read_b128 v[164:167], v182 offset:13312
	ds_read_b128 v[168:171], v182 offset:14336
	ds_read_b128 v[172:175], v182 offset:15360
	s_add_i32 s11, s10, 1
	v_cmp_eq_u32_e32 vcc, s11, v126
	s_waitcnt lgkmcnt(8)
	v_pk_mul_f32 v[112:113], v[46:47], v[130:131]
	v_pk_mul_f32 v[114:115], v[62:63], v[130:131]
	v_pk_mul_f32 v[116:117], v[78:79], v[130:131]
	v_pk_mul_f32 v[118:119], v[94:95], v[130:131]
	v_pk_fma_f32 v[112:113], v[48:49], v[128:129], v[112:113]
	v_pk_fma_f32 v[114:115], v[64:65], v[128:129], v[114:115]
	v_pk_fma_f32 v[116:117], v[80:81], v[128:129], v[116:117]
	v_pk_fma_f32 v[118:119], v[96:97], v[128:129], v[118:119]
	v_pk_fma_f32 v[112:113], v[50:51], v[134:135], v[112:113]
	v_pk_fma_f32 v[114:115], v[66:67], v[134:135], v[114:115]
	v_pk_fma_f32 v[116:117], v[82:83], v[134:135], v[116:117]
	v_pk_fma_f32 v[118:119], v[98:99], v[134:135], v[118:119]
	v_pk_fma_f32 v[112:113], v[52:53], v[132:133], v[112:113]
	v_pk_fma_f32 v[114:115], v[68:69], v[132:133], v[114:115]
	v_pk_fma_f32 v[116:117], v[84:85], v[132:133], v[116:117]
	v_pk_fma_f32 v[118:119], v[100:101], v[132:133], v[118:119]
	v_pk_fma_f32 v[112:113], v[54:55], v[138:139], v[112:113]
	v_pk_fma_f32 v[114:115], v[70:71], v[138:139], v[114:115]
	v_pk_fma_f32 v[116:117], v[86:87], v[138:139], v[116:117]
	v_pk_fma_f32 v[118:119], v[102:103], v[138:139], v[118:119]
	v_pk_fma_f32 v[112:113], v[56:57], v[136:137], v[112:113]
	v_pk_fma_f32 v[114:115], v[72:73], v[136:137], v[114:115]
	v_pk_fma_f32 v[116:117], v[88:89], v[136:137], v[116:117]
	v_pk_fma_f32 v[118:119], v[104:105], v[136:137], v[118:119]
	v_pk_fma_f32 v[112:113], v[58:59], v[142:143], v[112:113]
	v_pk_fma_f32 v[114:115], v[74:75], v[142:143], v[114:115]
	v_pk_fma_f32 v[116:117], v[90:91], v[142:143], v[116:117]
	v_pk_fma_f32 v[118:119], v[106:107], v[142:143], v[118:119]
	v_pk_fma_f32 v[112:113], v[60:61], v[140:141], v[112:113]
	v_pk_fma_f32 v[114:115], v[76:77], v[140:141], v[114:115]
	v_pk_fma_f32 v[116:117], v[92:93], v[140:141], v[116:117]
	v_pk_fma_f32 v[118:119], v[108:109], v[140:141], v[118:119]
	v_add_f32_e32 v122, v116, v117
	v_add_f32_e32 v123, v118, v119
	v_add_f32_e32 v120, v112, v113
	v_add_f32_e32 v121, v114, v115
	v_permlane32_swap_b32_e32 v122, v123
	s_nop 0
	v_permlane32_swap_b32_e32 v120, v121
	v_add_f32_e32 v125, v122, v123
	v_add_f32_e32 v124, v120, v121
	s_nop 0
	v_add_f32_dpp v125, v125, v125 quad_perm:[1,0,3,2] row_mask:0xf bank_mask:0xf bound_ctrl:1
	v_add_f32_dpp v124, v124, v124 quad_perm:[1,0,3,2] row_mask:0xf bank_mask:0xf bound_ctrl:1
	s_nop 0
	v_add_f32_dpp v125, v125, v125 quad_perm:[2,3,0,1] row_mask:0xf bank_mask:0xf bound_ctrl:1
	v_add_f32_dpp v124, v124, v124 quad_perm:[2,3,0,1] row_mask:0xf bank_mask:0xf bound_ctrl:1
	s_nop 0
	v_add_f32_dpp v125, v125, v125 row_half_mirror row_mask:0xf bank_mask:0xf bound_ctrl:1
	v_add_f32_dpp v124, v124, v124 row_half_mirror row_mask:0xf bank_mask:0xf bound_ctrl:1
	s_nop 0
	v_add_f32_dpp v125, v125, v125 row_mirror row_mask:0xf bank_mask:0xf bound_ctrl:1
	v_add_f32_dpp v124, v124, v124 row_mirror row_mask:0xf bank_mask:0xf bound_ctrl:1
	s_nop 0
	v_add_f32_dpp v125, v125, v125 row_bcast:15 row_mask:0xa bank_mask:0xf
	v_add_f32_dpp v124, v124, v124 row_bcast:15 row_mask:0xa bank_mask:0xf
	v_cndmask_b32_e32 v111, v111, v125, vcc
	v_cndmask_b32_e32 v110, v110, v124, vcc
	ds_read_b128 v[16:19], v182 offset:16384
	ds_read_b128 v[20:23], v182 offset:17408
	ds_read_b128 v[24:27], v182 offset:18432
	ds_read_b128 v[28:31], v182 offset:19456
	s_add_i32 s11, s10, 2
	v_cmp_eq_u32_e32 vcc, s11, v126
	s_waitcnt lgkmcnt(8)
; template <int RB> DI void norm_rows(float* X, const f32x4 (&gv)[4], bf16_t* XN, const float* wsm, float* SM, int row0, int lane, const float* part) {
;     ...
;         for (int jj = 0; jj < 24; ++jj) {
;             const f32x4* wr = (const f32x4*)(wsm + (size_t)jj * D); f32x4 w[4];
; #pragma unroll
;             for (int j = 0; j < 4; ++j) w[j] = wr[lane + 64 * j];
; #pragma unroll
;             for (int r = 0; r < RB; ++r) { float p = 0.f;
; #pragma unroll
;                 for (int j = 0; j < 4; ++j) p += (v[r][j][0] * w[j][0] + v[r][j][1] * w[j][1]) + (v[r][j][2] * w[j][2] + v[r][j][3] * w[j][3]);
;                 p = wave_sum(p); if (lane == jj) mine[r] = p; }
	v_pk_mul_f32 v[112:113], v[46:47], v[146:147]
	v_pk_mul_f32 v[114:115], v[62:63], v[146:147]
	v_pk_mul_f32 v[116:117], v[78:79], v[146:147]
	v_pk_mul_f32 v[118:119], v[94:95], v[146:147]
	v_pk_fma_f32 v[112:113], v[48:49], v[144:145], v[112:113]
	v_pk_fma_f32 v[114:115], v[64:65], v[144:145], v[114:115]
	v_pk_fma_f32 v[116:117], v[80:81], v[144:145], v[116:117]
	v_pk_fma_f32 v[118:119], v[96:97], v[144:145], v[118:119]
	v_pk_fma_f32 v[112:113], v[50:51], v[150:151], v[112:113]
	v_pk_fma_f32 v[114:115], v[66:67], v[150:151], v[114:115]
	v_pk_fma_f32 v[116:117], v[82:83], v[150:151], v[116:117]
	v_pk_fma_f32 v[118:119], v[98:99], v[150:151], v[118:119]
	v_pk_fma_f32 v[112:113], v[52:53], v[148:149], v[112:113]
	v_pk_fma_f32 v[114:115], v[68:69], v[148:149], v[114:115]
	v_pk_fma_f32 v[116:117], v[84:85], v[148:149], v[116:117]
	v_pk_fma_f32 v[118:119], v[100:101], v[148:149], v[118:119]
	v_pk_fma_f32 v[112:113], v[54:55], v[154:155], v[112:113]
	v_pk_fma_f32 v[114:115], v[70:71], v[154:155], v[114:115]
	v_pk_fma_f32 v[116:117], v[86:87], v[154:155], v[116:117]
	v_pk_fma_f32 v[118:119], v[102:103], v[154:155], v[118:119]
	v_pk_fma_f32 v[112:113], v[56:57], v[152:153], v[112:113]
	v_pk_fma_f32 v[114:115], v[72:73], v[152:153], v[114:115]
	v_pk_fma_f32 v[116:117], v[88:89], v[152:153], v[116:117]
	v_pk_fma_f32 v[118:119], v[104:105], v[152:153], v[118:119]
	v_pk_fma_f32 v[112:113], v[58:59], v[158:159], v[112:113]
	v_pk_fma_f32 v[114:115], v[74:75], v[158:159], v[114:115]
	v_pk_fma_f32 v[116:117], v[90:91], v[158:159], v[116:117]
	v_pk_fma_f32 v[118:119], v[106:107], v[158:159], v[118:119]
	v_pk_fma_f32 v[112:113], v[60:61], v[156:157], v[112:113]
	v_pk_fma_f32 v[114:115], v[76:77], v[156:157], v[114:115]
	v_pk_fma_f32 v[116:117], v[92:93], v[156:157], v[116:117]
	v_pk_fma_f32 v[118:119], v[108:109], v[156:157], v[118:119]
	v_add_f32_e32 v122, v116, v117
	v_add_f32_e32 v123, v118, v119
	v_add_f32_e32 v120, v112, v113
	v_add_f32_e32 v121, v114, v115
	v_permlane32_swap_b32_e32 v122, v123
	s_nop 0
	v_permlane32_swap_b32_e32 v120, v121
	v_add_f32_e32 v125, v122, v123
	v_add_f32_e32 v124, v120, v121
	s_nop 0
	v_add_f32_dpp v125, v125, v125 quad_perm:[1,0,3,2] row_mask:0xf bank_mask:0xf bound_ctrl:1
	v_add_f32_dpp v124, v124, v124 quad_perm:[1,0,3,2] row_mask:0xf bank_mask:0xf bound_ctrl:1
	s_nop 0
	v_add_f32_dpp v125, v125, v125 quad_perm:[2,3,0,1] row_mask:0xf bank_mask:0xf bound_ctrl:1
	v_add_f32_dpp v124, v124, v124 quad_perm:[2,3,0,1] row_mask:0xf bank_mask:0xf bound_ctrl:1
	s_nop 0
	v_add_f32_dpp v125, v125, v125 row_half_mirror row_mask:0xf bank_mask:0xf bound_ctrl:1
	v_add_f32_dpp v124, v124, v124 row_half_mirror row_mask:0xf bank_mask:0xf bound_ctrl:1
	s_nop 0
	v_add_f32_dpp v125, v125, v125 row_mirror row_mask:0xf bank_mask:0xf bound_ctrl:1
	v_add_f32_dpp v124, v124, v124 row_mirror row_mask:0xf bank_mask:0xf bound_ctrl:1
	s_nop 0
	v_add_f32_dpp v125, v125, v125 row_bcast:15 row_mask:0xa bank_mask:0xf
	v_add_f32_dpp v124, v124, v124 row_bcast:15 row_mask:0xa bank_mask:0xf
	v_cndmask_b32_e32 v111, v111, v125, vcc
	v_cndmask_b32_e32 v110, v110, v124, vcc
	ds_read_b128 v[128:131], v182 offset:20480
	ds_read_b128 v[132:135], v182 offset:21504
	ds_read_b128 v[136:139], v182 offset:22528
	ds_read_b128 v[140:143], v182 offset:23552
	s_add_i32 s11, s10, 3
	v_cmp_eq_u32_e32 vcc, s11, v126
	s_waitcnt lgkmcnt(8)
	v_pk_mul_f32 v[112:113], v[46:47], v[162:163]
	v_pk_mul_f32 v[114:115], v[62:63], v[162:163]
	v_pk_mul_f32 v[116:117], v[78:79], v[162:163]
	v_pk_mul_f32 v[118:119], v[94:95], v[162:163]
	v_pk_fma_f32 v[112:113], v[48:49], v[160:161], v[112:113]
	v_pk_fma_f32 v[114:115], v[64:65], v[160:161], v[114:115]
	v_pk_fma_f32 v[116:117], v[80:81], v[160:161], v[116:117]
	v_pk_fma_f32 v[118:119], v[96:97], v[160:161], v[118:119]
	v_pk_fma_f32 v[112:113], v[50:51], v[166:167], v[112:113]
	v_pk_fma_f32 v[114:115], v[66:67], v[166:167], v[114:115]
	v_pk_fma_f32 v[116:117], v[82:83], v[166:167], v[116:117]
	v_pk_fma_f32 v[118:119], v[98:99], v[166:167], v[118:119]
	v_pk_fma_f32 v[112:113], v[52:53], v[164:165], v[112:113]
	v_pk_fma_f32 v[114:115], v[68:69], v[164:165], v[114:115]
	v_pk_fma_f32 v[116:117], v[84:85], v[164:165], v[116:117]
	v_pk_fma_f32 v[118:119], v[100:101], v[164:165], v[118:119]
	v_pk_fma_f32 v[112:113], v[54:55], v[170:171], v[112:113]
	v_pk_fma_f32 v[114:115], v[70:71], v[170:171], v[114:115]
	v_pk_fma_f32 v[116:117], v[86:87], v[170:171], v[116:117]
	v_pk_fma_f32 v[118:119], v[102:103], v[170:171], v[118:119]
	v_pk_fma_f32 v[112:113], v[56:57], v[168:169], v[112:113]
	v_pk_fma_f32 v[114:115], v[72:73], v[168:169], v[114:115]
	v_pk_fma_f32 v[116:117], v[88:89], v[168:169], v[116:117]
	v_pk_fma_f32 v[118:119], v[104:105], v[168:169], v[118:119]
	v_pk_fma_f32 v[112:113], v[58:59], v[174:175], v[112:113]
	v_pk_fma_f32 v[114:115], v[74:75], v[174:175], v[114:115]
	v_pk_fma_f32 v[116:117], v[90:91], v[174:175], v[116:117]
	v_pk_fma_f32 v[118:119], v[106:107], v[174:175], v[118:119]
	v_pk_fma_f32 v[112:113], v[60:61], v[172:173], v[112:113]
	v_pk_fma_f32 v[114:115], v[76:77], v[172:173], v[114:115]
	v_pk_fma_f32 v[116:117], v[92:93], v[172:173], v[116:117]
	v_pk_fma_f32 v[118:119], v[108:109], v[172:173], v[118:119]
	v_add_f32_e32 v122, v116, v117
	v_add_f32_e32 v123, v118, v119
	v_add_f32_e32 v120, v112, v113
	v_add_f32_e32 v121, v114, v115
	v_permlane32_swap_b32_e32 v122, v123
	s_nop 0
	v_permlane32_swap_b32_e32 v120, v121
	v_add_f32_e32 v125, v122, v123
	v_add_f32_e32 v124, v120, v121
	s_nop 0
	v_add_f32_dpp v125, v125, v125 quad_perm:[1,0,3,2] row_mask:0xf bank_mask:0xf bound_ctrl:1
	v_add_f32_dpp v124, v124, v124 quad_perm:[1,0,3,2] row_mask:0xf bank_mask:0xf bound_ctrl:1
	s_nop 0
	v_add_f32_dpp v125, v125, v125 quad_perm:[2,3,0,1] row_mask:0xf bank_mask:0xf bound_ctrl:1
	v_add_f32_dpp v124, v124, v124 quad_perm:[2,3,0,1] row_mask:0xf bank_mask:0xf bound_ctrl:1
	s_nop 0
	v_add_f32_dpp v125, v125, v125 row_half_mirror row_mask:0xf bank_mask:0xf bound_ctrl:1
	v_add_f32_dpp v124, v124, v124 row_half_mirror row_mask:0xf bank_mask:0xf bound_ctrl:1
	s_nop 0
	v_add_f32_dpp v125, v125, v125 row_mirror row_mask:0xf bank_mask:0xf bound_ctrl:1
	v_add_f32_dpp v124, v124, v124 row_mirror row_mask:0xf bank_mask:0xf bound_ctrl:1
	s_nop 0
	v_add_f32_dpp v125, v125, v125 row_bcast:15 row_mask:0xa bank_mask:0xf
	v_add_f32_dpp v124, v124, v124 row_bcast:15 row_mask:0xa bank_mask:0xf
	v_cndmask_b32_e32 v111, v111, v125, vcc
	v_cndmask_b32_e32 v110, v110, v124, vcc
	s_cmp_eq_u32 s1, 3
	s_cbranch_scc0 .Lnp_nocopy
	v_mov_b32_e32 v32, v110
	v_mov_b32_e32 v43, v111
; template <int RB> DI void norm_rows(float* X, const f32x4 (&gv)[4], bf16_t* XN, const float* wsm, float* SM, int row0, int lane, const float* part) {
;     ...
;                 p = wave_sum(p); if (lane == jj) mine[r] = p; }
;         }
; #pragma unroll
;         for (int r = 0; r < RB; ++r) if (lane < 32) SM[(size_t)(row0 + r) * 32 + lane] = mine[r];
.Lnp_nocopy:
	v_add_u32_e32 v182, 0x4000, v182
	s_add_i32 s1, s1, 1
	s_cmp_eq_u32 s1, 6
	s_cbranch_scc0 .Lnp_trip
	s_waitcnt lgkmcnt(0)
	s_lshl_b64 s[2:3], s[6:7], 7
	v_lshl_add_u64 v[16:17], v[34:35], 0, s[2:3]
	s_mov_b32 exec_lo, 0xffff0000
	s_mov_b32 exec_hi, 0xffff0000
	global_store_dword v[16:17], v32, off offset:-64
	global_store_dword v[16:17], v43, off offset:192
	s_mov_b32 exec_lo, 0xff0000
	s_mov_b32 exec_hi, 0xff0000
	global_store_dword v[16:17], v110, off
	global_store_dword v[16:17], v111, off offset:256
	s_mov_b64 exec, -1
	s_mov_b64 s[20:21], -1
	s_branch .LBB0_943
